# P7 out_proj epilogue: rolling 14-deep xin prefetch instead of 48 serialized load-wait rounds
# speedup vs baseline: 1.0110x; 1.0110x over previous
.LBB0_1241:
	ds_read_b128 v[142:145], v155
	ds_read_b128 v[146:149], v155 offset:1024
	ds_read_b128 v[158:161], v155 offset:2048
	ds_read_b128 v[162:165], v155 offset:3072
	s_add_u32 s33, s36, 0xfffc0080
	s_addc_u32 s40, s37, -1
	s_cmp_eq_u32 s81, 12
	s_cselect_b32 s53, s29, s40
	s_cselect_b32 s52, s77, s33
	s_cselect_b32 s41, s27, s80
	s_cselect_b32 s40, s78, s79
	v_lshl_add_u64 v[150:151], s[36:37], 0, v[136:137]
	s_add_i32 m0, s58, 0xc000
	ds_read_b128 v[166:169], v156
	ds_read_b128 v[178:181], v156 offset:1024
	ds_read_b128 v[182:185], v156 offset:2048
	ds_read_b128 v[186:189], v156 offset:3072
	ds_read_b128 v[190:193], v156 offset:4096
	ds_read_b128 v[194:197], v156 offset:5120
	ds_read_b128 v[198:201], v156 offset:6144
	ds_read_b128 v[202:205], v156 offset:7168
	global_load_lds_dwordx4 v[150:151], off
	v_lshl_add_u64 v[150:151], s[36:37], 0, v[134:135]
	s_add_i32 m0, s58, 0xe000
	s_nop 0
	global_load_lds_dwordx4 v[150:151], off
	s_waitcnt lgkmcnt(8)
	s_barrier
	s_waitcnt lgkmcnt(0)
	s_setprio 1
	s_waitcnt lgkmcnt(0)
	v_mfma_f32_16x16x32_bf16 v[124:127], v[142:145], v[166:169], v[124:127]
	v_mfma_f32_16x16x32_bf16 v[120:123], v[158:161], v[166:169], v[120:123]
	v_mfma_f32_16x16x32_bf16 v[116:119], v[142:145], v[182:185], v[116:119]
	v_mfma_f32_16x16x32_bf16 v[112:115], v[158:161], v[182:185], v[112:115]
	v_mfma_f32_16x16x32_bf16 v[108:111], v[142:145], v[190:193], v[108:111]
	v_mfma_f32_16x16x32_bf16 v[104:107], v[158:161], v[190:193], v[104:107]
	v_mfma_f32_16x16x32_bf16 v[100:103], v[142:145], v[198:201], v[100:103]
	v_mfma_f32_16x16x32_bf16 v[96:99], v[158:161], v[198:201], v[96:99]
	v_mfma_f32_16x16x32_bf16 v[124:127], v[146:149], v[178:181], v[124:127]
	v_mfma_f32_16x16x32_bf16 v[120:123], v[162:165], v[178:181], v[120:123]
	v_mfma_f32_16x16x32_bf16 v[116:119], v[146:149], v[186:189], v[116:119]
	v_mfma_f32_16x16x32_bf16 v[112:115], v[162:165], v[186:189], v[112:115]
	v_mfma_f32_16x16x32_bf16 v[108:111], v[146:149], v[194:197], v[108:111]
	v_mfma_f32_16x16x32_bf16 v[104:107], v[162:165], v[194:197], v[104:107]
	v_mfma_f32_16x16x32_bf16 v[100:103], v[146:149], v[202:205], v[100:103]
	v_mfma_f32_16x16x32_bf16 v[96:99], v[162:165], v[202:205], v[96:99]
	s_setprio 0
	s_barrier
	s_add_i32 s33, s68, s57
	v_lshl_add_u64 v[150:151], s[40:41], 0, v[130:131]
	s_mov_b32 m0, s33
	ds_read_b128 v[206:209], v157
	ds_read_b128 v[210:213], v157 offset:1024
	ds_read_b128 v[214:217], v157 offset:2048
	ds_read_b128 v[218:221], v157 offset:3072
	global_load_lds_dwordx4 v[150:151], off
	v_lshl_add_u64 v[222:223], s[40:41], 0, v[128:129]
	s_add_i32 m0, s33, 0x2000
	s_nop 0
	global_load_lds_dwordx4 v[222:223], off
	s_barrier
	s_waitcnt lgkmcnt(0)
	s_setprio 1
	s_waitcnt lgkmcnt(0)
	v_mfma_f32_16x16x32_bf16 v[92:95], v[206:209], v[166:169], v[92:95]
	v_mfma_f32_16x16x32_bf16 v[88:91], v[214:217], v[166:169], v[88:91]
	v_mfma_f32_16x16x32_bf16 v[84:87], v[206:209], v[182:185], v[84:87]
	v_mfma_f32_16x16x32_bf16 v[80:83], v[214:217], v[182:185], v[80:83]
	v_mfma_f32_16x16x32_bf16 v[76:79], v[206:209], v[190:193], v[76:79]
	v_mfma_f32_16x16x32_bf16 v[72:75], v[214:217], v[190:193], v[72:75]
	v_mfma_f32_16x16x32_bf16 v[68:71], v[206:209], v[198:201], v[68:71]
	v_mfma_f32_16x16x32_bf16 v[64:67], v[214:217], v[198:201], v[64:67]
	v_mfma_f32_16x16x32_bf16 v[92:95], v[210:213], v[178:181], v[92:95]
	v_mfma_f32_16x16x32_bf16 v[88:91], v[218:221], v[178:181], v[88:91]
	v_mfma_f32_16x16x32_bf16 v[84:87], v[210:213], v[186:189], v[84:87]
	v_mfma_f32_16x16x32_bf16 v[80:83], v[218:221], v[186:189], v[80:83]
	v_mfma_f32_16x16x32_bf16 v[76:79], v[210:213], v[194:197], v[76:79]
	v_mfma_f32_16x16x32_bf16 v[72:75], v[218:221], v[194:197], v[72:75]
	v_mfma_f32_16x16x32_bf16 v[68:71], v[210:213], v[202:205], v[68:71]
	v_mfma_f32_16x16x32_bf16 v[64:67], v[218:221], v[202:205], v[64:67]
	s_setprio 0
	s_mov_b32 m0, s58
	v_lshl_add_u64 v[224:225], s[52:53], 0, v[130:131]
	s_barrier
	ds_read_b128 v[166:169], v156 offset:16384
	ds_read_b128 v[178:181], v156 offset:17408
	ds_read_b128 v[182:185], v156 offset:18432
	ds_read_b128 v[186:189], v156 offset:19456
	ds_read_b128 v[190:193], v156 offset:20480
	ds_read_b128 v[194:197], v156 offset:21504
	ds_read_b128 v[198:201], v156 offset:22528
	ds_read_b128 v[202:205], v156 offset:23552
	global_load_lds_dwordx4 v[224:225], off
	v_lshl_add_u64 v[226:227], s[52:53], 0, v[128:129]
	s_mov_b32 m0, s59
	s_nop 0
	global_load_lds_dwordx4 v[226:227], off
	s_barrier
	s_waitcnt lgkmcnt(0)
	s_setprio 1
	s_waitcnt lgkmcnt(0)
	v_mfma_f32_16x16x32_bf16 v[60:63], v[142:145], v[166:169], v[60:63]
	v_mfma_f32_16x16x32_bf16 v[56:59], v[158:161], v[166:169], v[56:59]
	v_mfma_f32_16x16x32_bf16 v[52:55], v[142:145], v[182:185], v[52:55]
	v_mfma_f32_16x16x32_bf16 v[48:51], v[158:161], v[182:185], v[48:51]
	v_mfma_f32_16x16x32_bf16 v[44:47], v[142:145], v[190:193], v[44:47]
	v_mfma_f32_16x16x32_bf16 v[40:43], v[158:161], v[190:193], v[40:43]
	v_mfma_f32_16x16x32_bf16 v[36:39], v[142:145], v[198:201], v[36:39]
	v_mfma_f32_16x16x32_bf16 v[32:35], v[158:161], v[198:201], v[32:35]
	v_mfma_f32_16x16x32_bf16 v[60:63], v[146:149], v[178:181], v[60:63]
	v_mfma_f32_16x16x32_bf16 v[56:59], v[162:165], v[178:181], v[56:59]
	v_mfma_f32_16x16x32_bf16 v[52:55], v[146:149], v[186:189], v[52:55]
	v_mfma_f32_16x16x32_bf16 v[48:51], v[162:165], v[186:189], v[48:51]
	v_mfma_f32_16x16x32_bf16 v[44:47], v[146:149], v[194:197], v[44:47]
	v_mfma_f32_16x16x32_bf16 v[40:43], v[162:165], v[194:197], v[40:43]
	v_mfma_f32_16x16x32_bf16 v[36:39], v[146:149], v[202:205], v[36:39]
	v_mfma_f32_16x16x32_bf16 v[32:35], v[162:165], v[202:205], v[32:35]
	s_setprio 0
	s_barrier
	s_add_u32 s82, s40, 0x40000
	s_addc_u32 s83, s41, 0
	s_add_i32 s33, s69, s57
	v_lshl_add_u64 v[142:143], s[82:83], 0, v[130:131]
	s_mov_b32 m0, s33
	s_nop 0
	global_load_lds_dwordx4 v[142:143], off
	v_lshl_add_u64 v[142:143], s[82:83], 0, v[128:129]
	s_add_i32 m0, s33, 0x2000
	s_nop 0
	global_load_lds_dwordx4 v[142:143], off
	s_waitcnt vmcnt(6)
	s_barrier
	s_setprio 1
	v_mfma_f32_16x16x32_bf16 v[28:31], v[206:209], v[166:169], v[28:31]
	v_mfma_f32_16x16x32_bf16 v[24:27], v[214:217], v[166:169], v[24:27]
	v_mfma_f32_16x16x32_bf16 v[20:23], v[206:209], v[182:185], v[20:23]
	v_mfma_f32_16x16x32_bf16 v[16:19], v[214:217], v[182:185], v[16:19]
	v_mfma_f32_16x16x32_bf16 v[12:15], v[206:209], v[190:193], v[12:15]
	v_mfma_f32_16x16x32_bf16 v[8:11], v[214:217], v[190:193], v[8:11]
	v_mfma_f32_16x16x32_bf16 v[4:7], v[206:209], v[198:201], v[4:7]
	v_mfma_f32_16x16x32_bf16 v[0:3], v[214:217], v[198:201], v[0:3]
	v_mfma_f32_16x16x32_bf16 v[28:31], v[210:213], v[178:181], v[28:31]
	v_mfma_f32_16x16x32_bf16 v[24:27], v[218:221], v[178:181], v[24:27]
	v_mfma_f32_16x16x32_bf16 v[20:23], v[210:213], v[186:189], v[20:23]
	v_mfma_f32_16x16x32_bf16 v[16:19], v[218:221], v[186:189], v[16:19]
	v_mfma_f32_16x16x32_bf16 v[12:15], v[210:213], v[194:197], v[12:15]
	v_mfma_f32_16x16x32_bf16 v[8:11], v[218:221], v[194:197], v[8:11]
	v_mfma_f32_16x16x32_bf16 v[4:7], v[210:213], v[202:205], v[4:7]
	v_mfma_f32_16x16x32_bf16 v[0:3], v[218:221], v[202:205], v[0:3]
	s_setprio 0
	s_add_i32 s33, 0, 0x18000
	v_add_u32_e32 v132, s33, v153
	s_barrier
	ds_read_b128 v[142:145], v132
	ds_read_b128 v[146:149], v132 offset:1024
	ds_read_b128 v[158:161], v132 offset:2048
	ds_read_b128 v[162:165], v132 offset:3072
	s_add_u32 s52, s52, 0x40000
	s_addc_u32 s53, s53, 0
	s_mov_b32 m0, s60
	v_lshl_add_u64 v[206:207], s[52:53], 0, v[130:131]
	ds_read_b128 v[166:169], v156 offset:32768
	ds_read_b128 v[178:181], v156 offset:33792
	ds_read_b128 v[182:185], v156 offset:34816
	ds_read_b128 v[186:189], v156 offset:35840
	ds_read_b128 v[190:193], v156 offset:36864
	ds_read_b128 v[194:197], v156 offset:37888
	ds_read_b128 v[198:201], v156 offset:38912
	ds_read_b128 v[202:205], v156 offset:39936
	global_load_lds_dwordx4 v[206:207], off
	v_lshl_add_u64 v[206:207], s[52:53], 0, v[128:129]
	s_mov_b32 m0, s61
	s_nop 0
	global_load_lds_dwordx4 v[206:207], off
	s_waitcnt lgkmcnt(8)
	s_barrier
	s_waitcnt lgkmcnt(0)
	s_setprio 1
	s_waitcnt lgkmcnt(0)
	v_mfma_f32_16x16x32_bf16 v[124:127], v[142:145], v[166:169], v[124:127]
	v_mfma_f32_16x16x32_bf16 v[120:123], v[158:161], v[166:169], v[120:123]
	v_mfma_f32_16x16x32_bf16 v[116:119], v[142:145], v[182:185], v[116:119]
	v_mfma_f32_16x16x32_bf16 v[112:115], v[158:161], v[182:185], v[112:115]
	v_mfma_f32_16x16x32_bf16 v[108:111], v[142:145], v[190:193], v[108:111]
	v_mfma_f32_16x16x32_bf16 v[104:107], v[158:161], v[190:193], v[104:107]
	v_mfma_f32_16x16x32_bf16 v[100:103], v[142:145], v[198:201], v[100:103]
	v_mfma_f32_16x16x32_bf16 v[96:99], v[158:161], v[198:201], v[96:99]
	v_mfma_f32_16x16x32_bf16 v[124:127], v[146:149], v[178:181], v[124:127]
	v_mfma_f32_16x16x32_bf16 v[120:123], v[162:165], v[178:181], v[120:123]
	v_mfma_f32_16x16x32_bf16 v[116:119], v[146:149], v[186:189], v[116:119]
	v_mfma_f32_16x16x32_bf16 v[112:115], v[162:165], v[186:189], v[112:115]
	v_mfma_f32_16x16x32_bf16 v[108:111], v[146:149], v[194:197], v[108:111]
	v_mfma_f32_16x16x32_bf16 v[104:107], v[162:165], v[194:197], v[104:107]
	v_mfma_f32_16x16x32_bf16 v[100:103], v[146:149], v[202:205], v[100:103]
	v_mfma_f32_16x16x32_bf16 v[96:99], v[162:165], v[202:205], v[96:99]
	s_setprio 0
	s_barrier
	s_add_i32 s52, 0, 0x1c000
	s_add_i32 s33, s33, s57
	v_add_u32_e32 v132, s52, v153
	v_lshl_add_u64 v[150:151], v[150:151], 0, s[16:17]
	s_mov_b32 m0, s33
	ds_read_b128 v[206:209], v132
	ds_read_b128 v[210:213], v132 offset:1024
	ds_read_b128 v[214:217], v132 offset:2048
	ds_read_b128 v[218:221], v132 offset:3072
	global_load_lds_dwordx4 v[150:151], off
	v_lshl_add_u64 v[150:151], v[222:223], 0, s[16:17]
	s_add_i32 m0, s33, 0x2000
	s_nop 0
	global_load_lds_dwordx4 v[150:151], off
	s_barrier
	s_waitcnt lgkmcnt(0)
	s_setprio 1
	s_waitcnt lgkmcnt(0)
	v_mfma_f32_16x16x32_bf16 v[92:95], v[206:209], v[166:169], v[92:95]
	v_mfma_f32_16x16x32_bf16 v[88:91], v[214:217], v[166:169], v[88:91]
	v_mfma_f32_16x16x32_bf16 v[84:87], v[206:209], v[182:185], v[84:87]
	v_mfma_f32_16x16x32_bf16 v[80:83], v[214:217], v[182:185], v[80:83]
	v_mfma_f32_16x16x32_bf16 v[76:79], v[206:209], v[190:193], v[76:79]
	v_mfma_f32_16x16x32_bf16 v[72:75], v[214:217], v[190:193], v[72:75]
	v_mfma_f32_16x16x32_bf16 v[68:71], v[206:209], v[198:201], v[68:71]
	v_mfma_f32_16x16x32_bf16 v[64:67], v[214:217], v[198:201], v[64:67]
	v_mfma_f32_16x16x32_bf16 v[92:95], v[210:213], v[178:181], v[92:95]
	v_mfma_f32_16x16x32_bf16 v[88:91], v[218:221], v[178:181], v[88:91]
	v_mfma_f32_16x16x32_bf16 v[84:87], v[210:213], v[186:189], v[84:87]
	v_mfma_f32_16x16x32_bf16 v[80:83], v[218:221], v[186:189], v[80:83]
	v_mfma_f32_16x16x32_bf16 v[76:79], v[210:213], v[194:197], v[76:79]
	v_mfma_f32_16x16x32_bf16 v[72:75], v[218:221], v[194:197], v[72:75]
	v_mfma_f32_16x16x32_bf16 v[68:71], v[210:213], v[202:205], v[68:71]
	v_mfma_f32_16x16x32_bf16 v[64:67], v[218:221], v[202:205], v[64:67]
	s_setprio 0
	s_mov_b32 m0, s62
	v_lshl_add_u64 v[150:151], v[224:225], 0, s[16:17]
	s_barrier
	ds_read_b128 v[166:169], v156 offset:49152
	ds_read_b128 v[178:181], v156 offset:50176
	ds_read_b128 v[182:185], v156 offset:51200
	ds_read_b128 v[186:189], v156 offset:52224
	ds_read_b128 v[190:193], v156 offset:53248
	ds_read_b128 v[194:197], v156 offset:54272
	ds_read_b128 v[198:201], v156 offset:55296
	ds_read_b128 v[202:205], v156 offset:56320
	global_load_lds_dwordx4 v[150:151], off
	v_lshl_add_u64 v[150:151], v[226:227], 0, s[16:17]
	s_mov_b32 m0, s63
	s_nop 0
	global_load_lds_dwordx4 v[150:151], off
	s_barrier
	s_waitcnt lgkmcnt(0)
	s_setprio 1
	s_waitcnt lgkmcnt(0)
	v_mfma_f32_16x16x32_bf16 v[60:63], v[142:145], v[166:169], v[60:63]
	v_mfma_f32_16x16x32_bf16 v[56:59], v[158:161], v[166:169], v[56:59]
	v_mfma_f32_16x16x32_bf16 v[52:55], v[142:145], v[182:185], v[52:55]
	v_mfma_f32_16x16x32_bf16 v[48:51], v[158:161], v[182:185], v[48:51]
	v_mfma_f32_16x16x32_bf16 v[44:47], v[142:145], v[190:193], v[44:47]
	v_mfma_f32_16x16x32_bf16 v[40:43], v[158:161], v[190:193], v[40:43]
	v_mfma_f32_16x16x32_bf16 v[36:39], v[142:145], v[198:201], v[36:39]
	v_mfma_f32_16x16x32_bf16 v[32:35], v[158:161], v[198:201], v[32:35]
	v_mfma_f32_16x16x32_bf16 v[60:63], v[146:149], v[178:181], v[60:63]
	v_mfma_f32_16x16x32_bf16 v[56:59], v[162:165], v[178:181], v[56:59]
	v_mfma_f32_16x16x32_bf16 v[52:55], v[146:149], v[186:189], v[52:55]
	v_mfma_f32_16x16x32_bf16 v[48:51], v[162:165], v[186:189], v[48:51]
	v_mfma_f32_16x16x32_bf16 v[44:47], v[146:149], v[194:197], v[44:47]
	v_mfma_f32_16x16x32_bf16 v[40:43], v[162:165], v[194:197], v[40:43]
	v_mfma_f32_16x16x32_bf16 v[36:39], v[146:149], v[202:205], v[36:39]
	v_mfma_f32_16x16x32_bf16 v[32:35], v[162:165], v[202:205], v[32:35]
	s_setprio 0
	s_barrier
	s_add_u32 s40, s40, 0x40080
	s_addc_u32 s41, s41, 0
	s_add_i32 s33, s52, s57
	v_lshl_add_u64 v[142:143], s[40:41], 0, v[130:131]
	s_mov_b32 m0, s33
	s_nop 0
	global_load_lds_dwordx4 v[142:143], off
	v_lshl_add_u64 v[142:143], s[40:41], 0, v[128:129]
	s_add_i32 m0, s33, 0x2000
	s_nop 0
	global_load_lds_dwordx4 v[142:143], off
	s_waitcnt vmcnt(6)
	s_barrier
	s_setprio 1
	v_mfma_f32_16x16x32_bf16 v[28:31], v[206:209], v[166:169], v[28:31]
	v_mfma_f32_16x16x32_bf16 v[24:27], v[214:217], v[166:169], v[24:27]
	v_mfma_f32_16x16x32_bf16 v[20:23], v[206:209], v[182:185], v[20:23]
	v_mfma_f32_16x16x32_bf16 v[16:19], v[214:217], v[182:185], v[16:19]
	v_mfma_f32_16x16x32_bf16 v[12:15], v[206:209], v[190:193], v[12:15]
	v_mfma_f32_16x16x32_bf16 v[8:11], v[214:217], v[190:193], v[8:11]
	v_mfma_f32_16x16x32_bf16 v[4:7], v[206:209], v[198:201], v[4:7]
	v_mfma_f32_16x16x32_bf16 v[0:3], v[214:217], v[198:201], v[0:3]
	v_mfma_f32_16x16x32_bf16 v[28:31], v[210:213], v[178:181], v[28:31]
	v_mfma_f32_16x16x32_bf16 v[24:27], v[218:221], v[178:181], v[24:27]
	v_mfma_f32_16x16x32_bf16 v[20:23], v[210:213], v[186:189], v[20:23]
	v_mfma_f32_16x16x32_bf16 v[16:19], v[218:221], v[186:189], v[16:19]
	v_mfma_f32_16x16x32_bf16 v[12:15], v[210:213], v[194:197], v[12:15]
	v_mfma_f32_16x16x32_bf16 v[8:11], v[218:221], v[194:197], v[8:11]
	v_mfma_f32_16x16x32_bf16 v[4:7], v[210:213], v[202:205], v[4:7]
	v_mfma_f32_16x16x32_bf16 v[0:3], v[218:221], v[202:205], v[0:3]
	s_setprio 0
	s_add_i32 s81, s81, 2
	s_add_u32 s79, s79, 0x100
	s_addc_u32 s80, s80, 0
	s_add_u32 s36, s36, 0x100
	s_addc_u32 s37, s37, 0
	s_cmp_gt_u32 s81, 13
	s_barrier
	s_cbranch_scc0 .LBB0_1241
	s_load_dwordx4 s[80:83], s[6:7], 0x0
	s_lshl_b32 s77, s10, 8
	v_lshl_or_b32 v142, s76, 8, v154
	v_add_u32_e32 v132, s77, v152
	v_lshlrev_b32_e32 v142, 2, v142
	s_sub_u32 s78, s77, 0x1000
	s_lshr_b32 s78, s78, 11
	s_mul_i32 s78, s78, 6
	s_add_i32 s78, s78, 8
	s_cmp_gt_i32 s10, 15
	s_cselect_b32 s78, s78, 2
	s_cselect_b32 s79, 0x1000000, 0
	s_lshl_b32 s78, s78, 12
	s_add_u32 s48, s66, s78
	s_addc_u32 s49, s67, 0
	v_lshl_add_u32 v143, v132, 12, v142
	global_load_dwordx4 v[144:147], v142, s[48:49]
	global_load_dwordx4 v[148:151], v142, s[48:49] offset:64
	global_load_dwordx4 v[158:161], v142, s[48:49] offset:512
	global_load_dwordx4 v[162:165], v142, s[48:49] offset:576
	s_mov_b64 s[86:87], s[12:13]
	s_cmp_gt_i32 s10, 15
	s_waitcnt lgkmcnt(0)
	s_cselect_b32 s84, s82, s80
	s_cselect_b32 s85, s83, s81
	s_sub_u32 s84, s84, s79
	s_subb_u32 s85, s85, 0
	global_load_dwordx4 v[178:181], v143, s[84:85]
	global_load_dwordx4 v[182:185], v143, s[84:85] offset:64
	global_load_dwordx4 v[186:189], v143, s[84:85] offset:512
	global_load_dwordx4 v[190:193], v143, s[84:85] offset:576
	s_add_u32 s84, s84, 0x10000
	s_addc_u32 s85, s85, 0
	global_load_dwordx4 v[194:197], v143, s[84:85]
	global_load_dwordx4 v[198:201], v143, s[84:85] offset:64
	global_load_dwordx4 v[202:205], v143, s[84:85] offset:512
	global_load_dwordx4 v[206:209], v143, s[84:85] offset:576
	s_add_u32 s84, s84, 0x10000
	s_addc_u32 s85, s85, 0
	global_load_dwordx4 v[210:213], v143, s[84:85]
	global_load_dwordx4 v[214:217], v143, s[84:85] offset:64
	global_load_dwordx4 v[218:221], v143, s[84:85] offset:512
	global_load_dwordx4 v[222:225], v143, s[84:85] offset:576
	s_add_u32 s84, s84, 0x10000
	s_addc_u32 s85, s85, 0
	global_load_dwordx4 v[226:229], v143, s[84:85]
	global_load_dwordx4 v[230:233], v143, s[84:85] offset:64
	s_waitcnt vmcnt(13)
	v_pk_fma_f32 v[124:125], v[124:125], v[144:145], v[178:179]
	v_pk_fma_f32 v[126:127], v[126:127], v[146:147], v[180:181]
	global_store_dwordx4 v143, v[124:127], s[86:87]
	global_load_dwordx4 v[178:181], v143, s[84:85] offset:512
	s_waitcnt vmcnt(14)
	v_pk_fma_f32 v[120:121], v[120:121], v[148:149], v[182:183]
	v_pk_fma_f32 v[122:123], v[122:123], v[150:151], v[184:185]
	global_store_dwordx4 v143, v[120:123], s[86:87] offset:64
	global_load_dwordx4 v[182:185], v143, s[84:85] offset:576
	s_waitcnt vmcnt(15)
	v_pk_fma_f32 v[92:93], v[92:93], v[158:159], v[186:187]
	v_pk_fma_f32 v[94:95], v[94:95], v[160:161], v[188:189]
	global_store_dwordx4 v143, v[92:95], s[86:87] offset:512
	s_add_u32 s84, s84, 0x50000
	s_addc_u32 s85, s85, 0
	global_load_dwordx4 v[186:189], v143, s[84:85]
	s_waitcnt vmcnt(16)
	v_pk_fma_f32 v[88:89], v[88:89], v[162:163], v[190:191]
	v_pk_fma_f32 v[90:91], v[90:91], v[164:165], v[192:193]
	global_store_dwordx4 v143, v[88:91], s[86:87] offset:576
	global_load_dwordx4 v[190:193], v143, s[84:85] offset:64
	s_add_u32 s86, s86, 0x10000
	s_addc_u32 s87, s87, 0
	s_waitcnt vmcnt(17)
	v_pk_fma_f32 v[116:117], v[116:117], v[144:145], v[194:195]
	v_pk_fma_f32 v[118:119], v[118:119], v[146:147], v[196:197]
	global_store_dwordx4 v143, v[116:119], s[86:87]
	global_load_dwordx4 v[194:197], v143, s[84:85] offset:512
	s_waitcnt vmcnt(18)
	v_pk_fma_f32 v[112:113], v[112:113], v[148:149], v[198:199]
	v_pk_fma_f32 v[114:115], v[114:115], v[150:151], v[200:201]
	global_store_dwordx4 v143, v[112:115], s[86:87] offset:64
	global_load_dwordx4 v[198:201], v143, s[84:85] offset:576
	s_waitcnt vmcnt(19)
	v_pk_fma_f32 v[84:85], v[84:85], v[158:159], v[202:203]
	v_pk_fma_f32 v[86:87], v[86:87], v[160:161], v[204:205]
	global_store_dwordx4 v143, v[84:87], s[86:87] offset:512
	s_add_u32 s84, s84, 0x10000
	s_addc_u32 s85, s85, 0
	global_load_dwordx4 v[202:205], v143, s[84:85]
	s_waitcnt vmcnt(20)
	v_pk_fma_f32 v[80:81], v[80:81], v[162:163], v[206:207]
	v_pk_fma_f32 v[82:83], v[82:83], v[164:165], v[208:209]
	global_store_dwordx4 v143, v[80:83], s[86:87] offset:576
	global_load_dwordx4 v[206:209], v143, s[84:85] offset:64
	s_add_u32 s86, s86, 0x10000
	s_addc_u32 s87, s87, 0
	s_waitcnt vmcnt(21)
	v_pk_fma_f32 v[108:109], v[108:109], v[144:145], v[210:211]
	v_pk_fma_f32 v[110:111], v[110:111], v[146:147], v[212:213]
	global_store_dwordx4 v143, v[108:111], s[86:87]
	global_load_dwordx4 v[210:213], v143, s[84:85] offset:512
	s_waitcnt vmcnt(22)
	v_pk_fma_f32 v[104:105], v[104:105], v[148:149], v[214:215]
	v_pk_fma_f32 v[106:107], v[106:107], v[150:151], v[216:217]
	global_store_dwordx4 v143, v[104:107], s[86:87] offset:64
	global_load_dwordx4 v[214:217], v143, s[84:85] offset:576
	s_waitcnt vmcnt(23)
	v_pk_fma_f32 v[76:77], v[76:77], v[158:159], v[218:219]
	v_pk_fma_f32 v[78:79], v[78:79], v[160:161], v[220:221]
	global_store_dwordx4 v143, v[76:79], s[86:87] offset:512
	s_add_u32 s84, s84, 0x10000
	s_addc_u32 s85, s85, 0
	global_load_dwordx4 v[218:221], v143, s[84:85]
	s_waitcnt vmcnt(24)
	v_pk_fma_f32 v[72:73], v[72:73], v[162:163], v[222:223]
	v_pk_fma_f32 v[74:75], v[74:75], v[164:165], v[224:225]
	global_store_dwordx4 v143, v[72:75], s[86:87] offset:576
	global_load_dwordx4 v[222:225], v143, s[84:85] offset:64
	s_add_u32 s86, s86, 0x10000
	s_addc_u32 s87, s87, 0
	s_waitcnt vmcnt(25)
	v_pk_fma_f32 v[100:101], v[100:101], v[144:145], v[226:227]
	v_pk_fma_f32 v[102:103], v[102:103], v[146:147], v[228:229]
	global_store_dwordx4 v143, v[100:103], s[86:87]
	global_load_dwordx4 v[226:229], v143, s[84:85] offset:512
	s_waitcnt vmcnt(26)
	v_pk_fma_f32 v[96:97], v[96:97], v[148:149], v[230:231]
	v_pk_fma_f32 v[98:99], v[98:99], v[150:151], v[232:233]
	global_store_dwordx4 v143, v[96:99], s[86:87] offset:64
	global_load_dwordx4 v[230:233], v143, s[84:85] offset:576
	s_waitcnt vmcnt(26)
	v_pk_fma_f32 v[68:69], v[68:69], v[158:159], v[178:179]
	v_pk_fma_f32 v[70:71], v[70:71], v[160:161], v[180:181]
	global_store_dwordx4 v143, v[68:71], s[86:87] offset:512
	s_add_u32 s84, s84, 0x10000
	s_addc_u32 s85, s85, 0
	global_load_dwordx4 v[178:181], v143, s[84:85]
	s_waitcnt vmcnt(26)
	v_pk_fma_f32 v[64:65], v[64:65], v[162:163], v[182:183]
	v_pk_fma_f32 v[66:67], v[66:67], v[164:165], v[184:185]
	global_store_dwordx4 v143, v[64:67], s[86:87] offset:576
	global_load_dwordx4 v[182:185], v143, s[84:85] offset:64
	s_add_u32 s86, s86, 0x50000
	s_addc_u32 s87, s87, 0
	s_waitcnt vmcnt(26)
	v_pk_fma_f32 v[60:61], v[60:61], v[144:145], v[186:187]
	v_pk_fma_f32 v[62:63], v[62:63], v[146:147], v[188:189]
	global_store_dwordx4 v143, v[60:63], s[86:87]
	global_load_dwordx4 v[186:189], v143, s[84:85] offset:512
	s_waitcnt vmcnt(26)
	v_pk_fma_f32 v[56:57], v[56:57], v[148:149], v[190:191]
	v_pk_fma_f32 v[58:59], v[58:59], v[150:151], v[192:193]
	global_store_dwordx4 v143, v[56:59], s[86:87] offset:64
	global_load_dwordx4 v[190:193], v143, s[84:85] offset:576
	s_waitcnt vmcnt(26)
	v_pk_fma_f32 v[28:29], v[28:29], v[158:159], v[194:195]
	v_pk_fma_f32 v[30:31], v[30:31], v[160:161], v[196:197]
	global_store_dwordx4 v143, v[28:31], s[86:87] offset:512
	s_waitcnt vmcnt(25)
	v_pk_fma_f32 v[24:25], v[24:25], v[162:163], v[198:199]
	v_pk_fma_f32 v[26:27], v[26:27], v[164:165], v[200:201]
	global_store_dwordx4 v143, v[24:27], s[86:87] offset:576
	s_add_u32 s86, s86, 0x10000
	s_addc_u32 s87, s87, 0
	s_waitcnt vmcnt(24)
	v_pk_fma_f32 v[52:53], v[52:53], v[144:145], v[202:203]
	v_pk_fma_f32 v[54:55], v[54:55], v[146:147], v[204:205]
	global_store_dwordx4 v143, v[52:55], s[86:87]
	s_waitcnt vmcnt(23)
	v_pk_fma_f32 v[48:49], v[48:49], v[148:149], v[206:207]
	v_pk_fma_f32 v[50:51], v[50:51], v[150:151], v[208:209]
	global_store_dwordx4 v143, v[48:51], s[86:87] offset:64
	s_waitcnt vmcnt(22)
	v_pk_fma_f32 v[20:21], v[20:21], v[158:159], v[210:211]
	v_pk_fma_f32 v[22:23], v[22:23], v[160:161], v[212:213]
	global_store_dwordx4 v143, v[20:23], s[86:87] offset:512
	s_waitcnt vmcnt(21)
	v_pk_fma_f32 v[16:17], v[16:17], v[162:163], v[214:215]
	v_pk_fma_f32 v[18:19], v[18:19], v[164:165], v[216:217]
	global_store_dwordx4 v143, v[16:19], s[86:87] offset:576
	s_add_u32 s86, s86, 0x10000
	s_addc_u32 s87, s87, 0
	s_waitcnt vmcnt(20)
	v_pk_fma_f32 v[44:45], v[44:45], v[144:145], v[218:219]
	v_pk_fma_f32 v[46:47], v[46:47], v[146:147], v[220:221]
	global_store_dwordx4 v143, v[44:47], s[86:87]
	s_waitcnt vmcnt(19)
	v_pk_fma_f32 v[40:41], v[40:41], v[148:149], v[222:223]
	v_pk_fma_f32 v[42:43], v[42:43], v[150:151], v[224:225]
	global_store_dwordx4 v143, v[40:43], s[86:87] offset:64
	s_waitcnt vmcnt(18)
	v_pk_fma_f32 v[12:13], v[12:13], v[158:159], v[226:227]
	v_pk_fma_f32 v[14:15], v[14:15], v[160:161], v[228:229]
	global_store_dwordx4 v143, v[12:15], s[86:87] offset:512
	s_waitcnt vmcnt(17)
	v_pk_fma_f32 v[8:9], v[8:9], v[162:163], v[230:231]
	v_pk_fma_f32 v[10:11], v[10:11], v[164:165], v[232:233]
	global_store_dwordx4 v143, v[8:11], s[86:87] offset:576
	s_add_u32 s86, s86, 0x10000
	s_addc_u32 s87, s87, 0
	s_waitcnt vmcnt(16)
	v_pk_fma_f32 v[36:37], v[36:37], v[144:145], v[178:179]
	v_pk_fma_f32 v[38:39], v[38:39], v[146:147], v[180:181]
	global_store_dwordx4 v143, v[36:39], s[86:87]
	s_waitcnt vmcnt(15)
	v_pk_fma_f32 v[32:33], v[32:33], v[148:149], v[182:183]
	v_pk_fma_f32 v[34:35], v[34:35], v[150:151], v[184:185]
	global_store_dwordx4 v143, v[32:35], s[86:87] offset:64
	s_waitcnt vmcnt(14)
	v_pk_fma_f32 v[4:5], v[4:5], v[158:159], v[186:187]
	v_pk_fma_f32 v[6:7], v[6:7], v[160:161], v[188:189]
	global_store_dwordx4 v143, v[4:7], s[86:87] offset:512
	s_waitcnt vmcnt(13)
	v_pk_fma_f32 v[0:1], v[0:1], v[162:163], v[190:191]
	v_pk_fma_f32 v[2:3], v[2:3], v[164:165], v[192:193]
	global_store_dwordx4 v143, v[0:3], s[86:87] offset:576
	s_mov_b32 s76, s26
	s_mov_b64 s[36:37], s[34:35]
	s_mov_b64 s[40:41], s[30:31]
	s_mov_b32 s10, s28
	s_and_b64 vcc, exec, s[4:5]
	s_cbranch_vccz .LBB0_1238
	s_waitcnt vmcnt(0)
	s_cmpk_gt_u32 s45, 0xff
	s_cbranch_scc1 .LBB0_1245
	s_barrier
